# f32-MFMA adaLN + the 36 conditioning loads of the silu pass issued together
# speedup vs baseline: 1.0062x; 1.0062x over previous
; DI void ada_item(int it, const float* cP, const float* cS, const float* wada, const float* bada, float* mod, LAS float* red, int tid, int wave, int lane) {
;     ...
;     for (int u = 0; u < 2; ++u) {
;         const int kb = 128 * wave + 64 * u;
; #pragma unroll 4
;         for (int b = 0; b < 36; ++b) { const float cv = b < 4 ? cP[b * 1024 + kb + lane] : cS[(b - 4) * 1024 + kb + lane]; cs[lane * 36 + b] = cv / (1.f + __expf(-cv)); }
;         asm volatile("s_waitcnt lgkmcnt(0)" ::: "memory");
.LBB0_706:
	s_or_b32 s13, s8, s18
	s_xor_b64 s[14:15], s[6:7], -1
	v_or_b32_e32 v36, s13, v207
	v_add_u32_e32 v37, s13, v87
	s_movk_i32 s20, 0xc00
	v_mov_b32_e32 v38, v85
	v_lshlrev_b32_e32 v39, 2, v36
	global_load_dword v112, v39, s[58:59]
	v_add_u32_e32 v39, 0x1000, v39
	global_load_dword v113, v39, s[58:59]
	v_add_u32_e32 v39, 0x1000, v39
	global_load_dword v114, v39, s[58:59]
	v_add_u32_e32 v39, 0x1000, v39
	global_load_dword v115, v39, s[58:59]
	v_lshlrev_b32_e32 v39, 2, v36
	global_load_dword v116, v39, s[60:61]
	v_add_u32_e32 v39, 0x1000, v39
	global_load_dword v117, v39, s[60:61]
	v_add_u32_e32 v39, 0x1000, v39
	global_load_dword v118, v39, s[60:61]
	v_add_u32_e32 v39, 0x1000, v39
	global_load_dword v119, v39, s[60:61]
	v_add_u32_e32 v39, 0x1000, v39
	global_load_dword v120, v39, s[60:61]
	v_add_u32_e32 v39, 0x1000, v39
	global_load_dword v121, v39, s[60:61]
	v_add_u32_e32 v39, 0x1000, v39
	global_load_dword v122, v39, s[60:61]
	v_add_u32_e32 v39, 0x1000, v39
	global_load_dword v123, v39, s[60:61]
	v_add_u32_e32 v39, 0x1000, v39
	global_load_dword v124, v39, s[60:61]
	v_add_u32_e32 v39, 0x1000, v39
	global_load_dword v125, v39, s[60:61]
	v_add_u32_e32 v39, 0x1000, v39
	global_load_dword v126, v39, s[60:61]
	v_add_u32_e32 v39, 0x1000, v39
	global_load_dword v127, v39, s[60:61]
	v_add_u32_e32 v39, 0x1000, v39
	global_load_dword v128, v39, s[60:61]
	v_add_u32_e32 v39, 0x1000, v39
	global_load_dword v129, v39, s[60:61]
	v_add_u32_e32 v39, 0x1000, v39
	global_load_dword v130, v39, s[60:61]
	v_add_u32_e32 v39, 0x1000, v39
	global_load_dword v131, v39, s[60:61]
	v_add_u32_e32 v39, 0x1000, v39
	global_load_dword v132, v39, s[60:61]
	v_add_u32_e32 v39, 0x1000, v39
	global_load_dword v133, v39, s[60:61]
	v_add_u32_e32 v39, 0x1000, v39
	global_load_dword v134, v39, s[60:61]
	v_add_u32_e32 v39, 0x1000, v39
	global_load_dword v135, v39, s[60:61]
	v_add_u32_e32 v39, 0x1000, v39
	global_load_dword v136, v39, s[60:61]
	v_add_u32_e32 v39, 0x1000, v39
	global_load_dword v137, v39, s[60:61]
	v_add_u32_e32 v39, 0x1000, v39
	global_load_dword v138, v39, s[60:61]
	v_add_u32_e32 v39, 0x1000, v39
	global_load_dword v139, v39, s[60:61]
	v_add_u32_e32 v39, 0x1000, v39
	global_load_dword v140, v39, s[60:61]
	v_add_u32_e32 v39, 0x1000, v39
	global_load_dword v141, v39, s[60:61]
	v_add_u32_e32 v39, 0x1000, v39
	global_load_dword v142, v39, s[60:61]
	v_add_u32_e32 v39, 0x1000, v39
	global_load_dword v143, v39, s[60:61]
	v_add_u32_e32 v39, 0x1000, v39
	global_load_dword v144, v39, s[60:61]
	v_add_u32_e32 v39, 0x1000, v39
	global_load_dword v145, v39, s[60:61]
	v_add_u32_e32 v39, 0x1000, v39
	global_load_dword v146, v39, s[60:61]
	v_add_u32_e32 v39, 0x1000, v39
	global_load_dword v147, v39, s[60:61]
	s_waitcnt vmcnt(0)
	v_mov_b32_e32 v39, v112
	v_mov_b32_e32 v42, v113
	v_mov_b32_e32 v43, v114
	v_mov_b32_e32 v44, v115
	s_waitcnt vmcnt(3)
	v_mul_f32_e32 v40, 0xbfb8aa3b, v39
	s_waitcnt vmcnt(2)
	v_mul_f32_e32 v41, 0xbfb8aa3b, v42
	v_exp_f32_e32 v40, v40
	s_waitcnt vmcnt(1)
	v_mul_f32_e32 v45, 0xbfb8aa3b, v43
	v_exp_f32_e32 v41, v41
	s_waitcnt vmcnt(0)
	v_mul_f32_e32 v46, 0xbfb8aa3b, v44
	v_exp_f32_e32 v45, v45
	v_exp_f32_e32 v46, v46
	v_add_f32_e32 v40, 1.0, v40
	v_add_f32_e32 v41, 1.0, v41
	v_div_scale_f32 v47, s[6:7], v40, v40, v39
	v_add_f32_e32 v45, 1.0, v45
	v_div_scale_f32 v49, s[6:7], v41, v41, v42
	v_rcp_f32_e32 v55, v47
	v_add_f32_e32 v46, 1.0, v46
	v_div_scale_f32 v51, s[8:9], v45, v45, v43
	v_rcp_f32_e32 v56, v49
	v_div_scale_f32 v53, s[10:11], v46, v46, v44
	v_rcp_f32_e32 v57, v51
	v_rcp_f32_e32 v58, v53
	v_fma_f32 v59, -v47, v55, 1.0
	v_div_scale_f32 v48, vcc, v39, v40, v39
	v_fma_f32 v60, -v49, v56, 1.0
	v_fmac_f32_e32 v55, v59, v55
	v_div_scale_f32 v50, s[6:7], v42, v41, v42
	v_fma_f32 v61, -v51, v57, 1.0
	v_fmac_f32_e32 v56, v60, v56
	v_mul_f32_e32 v59, v48, v55
	v_div_scale_f32 v52, s[8:9], v43, v45, v43
	v_fma_f32 v62, -v53, v58, 1.0
	v_fmac_f32_e32 v57, v61, v57
	v_mul_f32_e32 v60, v50, v56
	v_fma_f32 v63, -v47, v59, v48
	v_div_scale_f32 v54, s[10:11], v44, v46, v44
	v_fmac_f32_e32 v58, v62, v58
	v_mul_f32_e32 v61, v52, v57
	v_fma_f32 v64, -v49, v60, v50
	v_fmac_f32_e32 v59, v63, v55
	v_mul_f32_e32 v62, v54, v58
	v_fma_f32 v65, -v51, v61, v52
	v_fmac_f32_e32 v60, v64, v56
	v_fma_f32 v47, -v47, v59, v48
	v_fma_f32 v66, -v53, v62, v54
	v_fmac_f32_e32 v61, v65, v57
	v_fma_f32 v48, -v49, v60, v50
	v_div_fmas_f32 v47, v47, v55, v59
	s_mov_b64 vcc, s[6:7]
	v_fmac_f32_e32 v62, v66, v58
	v_fma_f32 v49, -v51, v61, v52
	v_div_fixup_f32 v40, v47, v40, v39
	v_div_fmas_f32 v39, v48, v56, v60
	s_mov_b64 vcc, s[8:9]
	v_fma_f32 v50, -v53, v62, v54
	v_div_fixup_f32 v41, v39, v41, v42
	v_div_fmas_f32 v39, v49, v57, v61
	s_mov_b64 vcc, s[10:11]
	v_div_fixup_f32 v42, v39, v45, v43
	v_div_fmas_f32 v39, v50, v58, v62
	v_div_fixup_f32 v43, v39, v46, v44
	ds_write_b128 v38, v[40:43]
	v_add_u32_e32 v38, 16, v38
	v_mov_b32_e32 v39, v116
	v_mov_b32_e32 v42, v117
	v_mov_b32_e32 v43, v118
	v_mov_b32_e32 v44, v119
	s_waitcnt vmcnt(3)
	v_mul_f32_e32 v40, 0xbfb8aa3b, v39
	s_waitcnt vmcnt(2)
	v_mul_f32_e32 v41, 0xbfb8aa3b, v42
	v_exp_f32_e32 v40, v40
	s_waitcnt vmcnt(1)
	v_mul_f32_e32 v45, 0xbfb8aa3b, v43
	v_exp_f32_e32 v41, v41
	s_waitcnt vmcnt(0)
; DI void ada_item(int it, const float* cP, const float* cS, const float* wada, const float* bada, float* mod, LAS float* red, int tid, int wave, int lane) {
;     ...
;         for (int b = 0; b < 36; ++b) { const float cv = b < 4 ? cP[b * 1024 + kb + lane] : cS[(b - 4) * 1024 + kb + lane]; cs[lane * 36 + b] = cv / (1.f + __expf(-cv)); }
;         asm volatile("s_waitcnt lgkmcnt(0)" ::: "memory");
	v_mul_f32_e32 v46, 0xbfb8aa3b, v44
	v_exp_f32_e32 v45, v45
	v_exp_f32_e32 v46, v46
	v_add_f32_e32 v40, 1.0, v40
	v_add_f32_e32 v41, 1.0, v41
	v_div_scale_f32 v47, s[6:7], v40, v40, v39
	v_add_f32_e32 v45, 1.0, v45
	v_div_scale_f32 v49, s[6:7], v41, v41, v42
	v_rcp_f32_e32 v55, v47
	v_add_f32_e32 v46, 1.0, v46
	v_div_scale_f32 v51, s[8:9], v45, v45, v43
	v_rcp_f32_e32 v56, v49
	v_div_scale_f32 v53, s[10:11], v46, v46, v44
	v_rcp_f32_e32 v57, v51
	v_rcp_f32_e32 v58, v53
	v_fma_f32 v59, -v47, v55, 1.0
	v_div_scale_f32 v48, vcc, v39, v40, v39
	v_fma_f32 v60, -v49, v56, 1.0
	v_fmac_f32_e32 v55, v59, v55
	v_div_scale_f32 v50, s[6:7], v42, v41, v42
	v_fma_f32 v61, -v51, v57, 1.0
	v_fmac_f32_e32 v56, v60, v56
	v_mul_f32_e32 v59, v48, v55
	v_div_scale_f32 v52, s[8:9], v43, v45, v43
	v_fma_f32 v62, -v53, v58, 1.0
	v_fmac_f32_e32 v57, v61, v57
	v_mul_f32_e32 v60, v50, v56
	v_fma_f32 v63, -v47, v59, v48
	v_div_scale_f32 v54, s[10:11], v44, v46, v44
	v_fmac_f32_e32 v58, v62, v58
	v_mul_f32_e32 v61, v52, v57
	v_fma_f32 v64, -v49, v60, v50
	v_fmac_f32_e32 v59, v63, v55
	v_mul_f32_e32 v62, v54, v58
	v_fma_f32 v65, -v51, v61, v52
	v_fmac_f32_e32 v60, v64, v56
	v_fma_f32 v47, -v47, v59, v48
	v_fma_f32 v66, -v53, v62, v54
	v_fmac_f32_e32 v61, v65, v57
	v_fma_f32 v48, -v49, v60, v50
	v_div_fmas_f32 v47, v47, v55, v59
	s_mov_b64 vcc, s[6:7]
	v_fmac_f32_e32 v62, v66, v58
	v_fma_f32 v49, -v51, v61, v52
	v_div_fixup_f32 v40, v47, v40, v39
	v_div_fmas_f32 v39, v48, v56, v60
	s_mov_b64 vcc, s[8:9]
	v_fma_f32 v50, -v53, v62, v54
	v_div_fixup_f32 v41, v39, v41, v42
	v_div_fmas_f32 v39, v49, v57, v61
	s_mov_b64 vcc, s[10:11]
	v_div_fixup_f32 v42, v39, v45, v43
	v_div_fmas_f32 v39, v50, v58, v62
	v_div_fixup_f32 v43, v39, v46, v44
	ds_write_b128 v38, v[40:43]
	v_add_u32_e32 v38, 16, v38
	v_mov_b32_e32 v39, v120
	v_mov_b32_e32 v42, v121
	v_mov_b32_e32 v43, v122
	v_mov_b32_e32 v44, v123
	s_waitcnt vmcnt(3)
	v_mul_f32_e32 v40, 0xbfb8aa3b, v39
	s_waitcnt vmcnt(2)
	v_mul_f32_e32 v41, 0xbfb8aa3b, v42
	v_exp_f32_e32 v40, v40
	s_waitcnt vmcnt(1)
	v_mul_f32_e32 v45, 0xbfb8aa3b, v43
	v_exp_f32_e32 v41, v41
	s_waitcnt vmcnt(0)
	v_mul_f32_e32 v46, 0xbfb8aa3b, v44
	v_exp_f32_e32 v45, v45
	v_exp_f32_e32 v46, v46
	v_add_f32_e32 v40, 1.0, v40
	v_add_f32_e32 v41, 1.0, v41
	v_div_scale_f32 v47, s[6:7], v40, v40, v39
	v_add_f32_e32 v45, 1.0, v45
	v_div_scale_f32 v49, s[6:7], v41, v41, v42
	v_rcp_f32_e32 v55, v47
	v_add_f32_e32 v46, 1.0, v46
	v_div_scale_f32 v51, s[8:9], v45, v45, v43
	v_rcp_f32_e32 v56, v49
	v_div_scale_f32 v53, s[10:11], v46, v46, v44
	v_rcp_f32_e32 v57, v51
	v_rcp_f32_e32 v58, v53
	v_fma_f32 v59, -v47, v55, 1.0
	v_div_scale_f32 v48, vcc, v39, v40, v39
	v_fma_f32 v60, -v49, v56, 1.0
	v_fmac_f32_e32 v55, v59, v55
	v_div_scale_f32 v50, s[6:7], v42, v41, v42
	v_fma_f32 v61, -v51, v57, 1.0
	v_fmac_f32_e32 v56, v60, v56
	v_mul_f32_e32 v59, v48, v55
	v_div_scale_f32 v52, s[8:9], v43, v45, v43
	v_fma_f32 v62, -v53, v58, 1.0
	v_fmac_f32_e32 v57, v61, v57
	v_mul_f32_e32 v60, v50, v56
	v_fma_f32 v63, -v47, v59, v48
	v_div_scale_f32 v54, s[10:11], v44, v46, v44
	v_fmac_f32_e32 v58, v62, v58
	v_mul_f32_e32 v61, v52, v57
	v_fma_f32 v64, -v49, v60, v50
	v_fmac_f32_e32 v59, v63, v55
	v_mul_f32_e32 v62, v54, v58
	v_fma_f32 v65, -v51, v61, v52
	v_fmac_f32_e32 v60, v64, v56
	v_fma_f32 v47, -v47, v59, v48
	v_fma_f32 v66, -v53, v62, v54
	v_fmac_f32_e32 v61, v65, v57
	v_fma_f32 v48, -v49, v60, v50
	v_div_fmas_f32 v47, v47, v55, v59
	s_mov_b64 vcc, s[6:7]
	v_fmac_f32_e32 v62, v66, v58
	v_fma_f32 v49, -v51, v61, v52
	v_div_fixup_f32 v40, v47, v40, v39
	v_div_fmas_f32 v39, v48, v56, v60
	s_mov_b64 vcc, s[8:9]
	v_fma_f32 v50, -v53, v62, v54
	v_div_fixup_f32 v41, v39, v41, v42
	v_div_fmas_f32 v39, v49, v57, v61
	s_mov_b64 vcc, s[10:11]
	v_div_fixup_f32 v42, v39, v45, v43
	v_div_fmas_f32 v39, v50, v58, v62
	v_div_fixup_f32 v43, v39, v46, v44
	ds_write_b128 v38, v[40:43]
	v_add_u32_e32 v38, 16, v38
	v_mov_b32_e32 v39, v124
	v_mov_b32_e32 v42, v125
	v_mov_b32_e32 v43, v126
	v_mov_b32_e32 v44, v127
	s_waitcnt vmcnt(3)
	v_mul_f32_e32 v40, 0xbfb8aa3b, v39
	s_waitcnt vmcnt(2)
	v_mul_f32_e32 v41, 0xbfb8aa3b, v42
	v_exp_f32_e32 v40, v40
	s_waitcnt vmcnt(1)
	v_mul_f32_e32 v45, 0xbfb8aa3b, v43
	v_exp_f32_e32 v41, v41
	s_waitcnt vmcnt(0)
	v_mul_f32_e32 v46, 0xbfb8aa3b, v44
	v_exp_f32_e32 v45, v45
	v_exp_f32_e32 v46, v46
	v_add_f32_e32 v40, 1.0, v40
	v_add_f32_e32 v41, 1.0, v41
	v_div_scale_f32 v47, s[6:7], v40, v40, v39
	v_add_f32_e32 v45, 1.0, v45
	v_div_scale_f32 v49, s[6:7], v41, v41, v42
	v_rcp_f32_e32 v55, v47
	v_add_f32_e32 v46, 1.0, v46
	v_div_scale_f32 v51, s[8:9], v45, v45, v43
	v_rcp_f32_e32 v56, v49
	v_div_scale_f32 v53, s[10:11], v46, v46, v44
	v_rcp_f32_e32 v57, v51
	v_rcp_f32_e32 v58, v53
	v_fma_f32 v59, -v47, v55, 1.0
	v_div_scale_f32 v48, vcc, v39, v40, v39
	v_fma_f32 v60, -v49, v56, 1.0
	v_fmac_f32_e32 v55, v59, v55
	v_div_scale_f32 v50, s[6:7], v42, v41, v42
	v_fma_f32 v61, -v51, v57, 1.0
	v_fmac_f32_e32 v56, v60, v56
	v_mul_f32_e32 v59, v48, v55
	v_div_scale_f32 v52, s[8:9], v43, v45, v43
	v_fma_f32 v62, -v53, v58, 1.0
	v_fmac_f32_e32 v57, v61, v57
	v_mul_f32_e32 v60, v50, v56
	v_fma_f32 v63, -v47, v59, v48
	v_div_scale_f32 v54, s[10:11], v44, v46, v44
	v_fmac_f32_e32 v58, v62, v58
	v_mul_f32_e32 v61, v52, v57
	v_fma_f32 v64, -v49, v60, v50
	v_fmac_f32_e32 v59, v63, v55
	v_mul_f32_e32 v62, v54, v58
	v_fma_f32 v65, -v51, v61, v52
	v_fmac_f32_e32 v60, v64, v56
	v_fma_f32 v47, -v47, v59, v48
	v_fma_f32 v66, -v53, v62, v54
	v_fmac_f32_e32 v61, v65, v57
	v_fma_f32 v48, -v49, v60, v50
	v_div_fmas_f32 v47, v47, v55, v59
	s_mov_b64 vcc, s[6:7]
	v_fmac_f32_e32 v62, v66, v58
	v_fma_f32 v49, -v51, v61, v52
	v_div_fixup_f32 v40, v47, v40, v39
	v_div_fmas_f32 v39, v48, v56, v60
	s_mov_b64 vcc, s[8:9]
	v_fma_f32 v50, -v53, v62, v54
	v_div_fixup_f32 v41, v39, v41, v42
	v_div_fmas_f32 v39, v49, v57, v61
	s_mov_b64 vcc, s[10:11]
	v_div_fixup_f32 v42, v39, v45, v43
	v_div_fmas_f32 v39, v50, v58, v62
	v_div_fixup_f32 v43, v39, v46, v44
	ds_write_b128 v38, v[40:43]
	v_add_u32_e32 v38, 16, v38
	v_mov_b32_e32 v39, v128
	v_mov_b32_e32 v42, v129
	v_mov_b32_e32 v43, v130
	v_mov_b32_e32 v44, v131
	s_waitcnt vmcnt(3)
; DI void ada_item(int it, const float* cP, const float* cS, const float* wada, const float* bada, float* mod, LAS float* red, int tid, int wave, int lane) {
;     ...
;         for (int b = 0; b < 36; ++b) { const float cv = b < 4 ? cP[b * 1024 + kb + lane] : cS[(b - 4) * 1024 + kb + lane]; cs[lane * 36 + b] = cv / (1.f + __expf(-cv)); }
;         asm volatile("s_waitcnt lgkmcnt(0)" ::: "memory");
	v_mul_f32_e32 v40, 0xbfb8aa3b, v39
	s_waitcnt vmcnt(2)
	v_mul_f32_e32 v41, 0xbfb8aa3b, v42
	v_exp_f32_e32 v40, v40
	s_waitcnt vmcnt(1)
	v_mul_f32_e32 v45, 0xbfb8aa3b, v43
	v_exp_f32_e32 v41, v41
	s_waitcnt vmcnt(0)
	v_mul_f32_e32 v46, 0xbfb8aa3b, v44
	v_exp_f32_e32 v45, v45
	v_exp_f32_e32 v46, v46
	v_add_f32_e32 v40, 1.0, v40
	v_add_f32_e32 v41, 1.0, v41
	v_div_scale_f32 v47, s[6:7], v40, v40, v39
	v_add_f32_e32 v45, 1.0, v45
	v_div_scale_f32 v49, s[6:7], v41, v41, v42
	v_rcp_f32_e32 v55, v47
	v_add_f32_e32 v46, 1.0, v46
	v_div_scale_f32 v51, s[8:9], v45, v45, v43
	v_rcp_f32_e32 v56, v49
	v_div_scale_f32 v53, s[10:11], v46, v46, v44
	v_rcp_f32_e32 v57, v51
	v_rcp_f32_e32 v58, v53
	v_fma_f32 v59, -v47, v55, 1.0
	v_div_scale_f32 v48, vcc, v39, v40, v39
	v_fma_f32 v60, -v49, v56, 1.0
	v_fmac_f32_e32 v55, v59, v55
	v_div_scale_f32 v50, s[6:7], v42, v41, v42
	v_fma_f32 v61, -v51, v57, 1.0
	v_fmac_f32_e32 v56, v60, v56
	v_mul_f32_e32 v59, v48, v55
	v_div_scale_f32 v52, s[8:9], v43, v45, v43
	v_fma_f32 v62, -v53, v58, 1.0
	v_fmac_f32_e32 v57, v61, v57
	v_mul_f32_e32 v60, v50, v56
	v_fma_f32 v63, -v47, v59, v48
	v_div_scale_f32 v54, s[10:11], v44, v46, v44
	v_fmac_f32_e32 v58, v62, v58
	v_mul_f32_e32 v61, v52, v57
	v_fma_f32 v64, -v49, v60, v50
	v_fmac_f32_e32 v59, v63, v55
	v_mul_f32_e32 v62, v54, v58
	v_fma_f32 v65, -v51, v61, v52
	v_fmac_f32_e32 v60, v64, v56
	v_fma_f32 v47, -v47, v59, v48
	v_fma_f32 v66, -v53, v62, v54
	v_fmac_f32_e32 v61, v65, v57
	v_fma_f32 v48, -v49, v60, v50
	v_div_fmas_f32 v47, v47, v55, v59
	s_mov_b64 vcc, s[6:7]
	v_fmac_f32_e32 v62, v66, v58
	v_fma_f32 v49, -v51, v61, v52
	v_div_fixup_f32 v40, v47, v40, v39
	v_div_fmas_f32 v39, v48, v56, v60
	s_mov_b64 vcc, s[8:9]
	v_fma_f32 v50, -v53, v62, v54
	v_div_fixup_f32 v41, v39, v41, v42
	v_div_fmas_f32 v39, v49, v57, v61
	s_mov_b64 vcc, s[10:11]
	v_div_fixup_f32 v42, v39, v45, v43
	v_div_fmas_f32 v39, v50, v58, v62
	v_div_fixup_f32 v43, v39, v46, v44
	ds_write_b128 v38, v[40:43]
	v_add_u32_e32 v38, 16, v38
	v_mov_b32_e32 v39, v132
	v_mov_b32_e32 v42, v133
	v_mov_b32_e32 v43, v134
	v_mov_b32_e32 v44, v135
	s_waitcnt vmcnt(3)
	v_mul_f32_e32 v40, 0xbfb8aa3b, v39
	s_waitcnt vmcnt(2)
	v_mul_f32_e32 v41, 0xbfb8aa3b, v42
	v_exp_f32_e32 v40, v40
	s_waitcnt vmcnt(1)
	v_mul_f32_e32 v45, 0xbfb8aa3b, v43
	v_exp_f32_e32 v41, v41
	s_waitcnt vmcnt(0)
	v_mul_f32_e32 v46, 0xbfb8aa3b, v44
	v_exp_f32_e32 v45, v45
	v_exp_f32_e32 v46, v46
	v_add_f32_e32 v40, 1.0, v40
	v_add_f32_e32 v41, 1.0, v41
	v_div_scale_f32 v47, s[6:7], v40, v40, v39
	v_add_f32_e32 v45, 1.0, v45
	v_div_scale_f32 v49, s[6:7], v41, v41, v42
	v_rcp_f32_e32 v55, v47
	v_add_f32_e32 v46, 1.0, v46
	v_div_scale_f32 v51, s[8:9], v45, v45, v43
	v_rcp_f32_e32 v56, v49
	v_div_scale_f32 v53, s[10:11], v46, v46, v44
	v_rcp_f32_e32 v57, v51
	v_rcp_f32_e32 v58, v53
	v_fma_f32 v59, -v47, v55, 1.0
	v_div_scale_f32 v48, vcc, v39, v40, v39
	v_fma_f32 v60, -v49, v56, 1.0
	v_fmac_f32_e32 v55, v59, v55
	v_div_scale_f32 v50, s[6:7], v42, v41, v42
	v_fma_f32 v61, -v51, v57, 1.0
	v_fmac_f32_e32 v56, v60, v56
	v_mul_f32_e32 v59, v48, v55
	v_div_scale_f32 v52, s[8:9], v43, v45, v43
	v_fma_f32 v62, -v53, v58, 1.0
	v_fmac_f32_e32 v57, v61, v57
	v_mul_f32_e32 v60, v50, v56
	v_fma_f32 v63, -v47, v59, v48
	v_div_scale_f32 v54, s[10:11], v44, v46, v44
	v_fmac_f32_e32 v58, v62, v58
	v_mul_f32_e32 v61, v52, v57
	v_fma_f32 v64, -v49, v60, v50
	v_fmac_f32_e32 v59, v63, v55
	v_mul_f32_e32 v62, v54, v58
	v_fma_f32 v65, -v51, v61, v52
	v_fmac_f32_e32 v60, v64, v56
	v_fma_f32 v47, -v47, v59, v48
	v_fma_f32 v66, -v53, v62, v54
	v_fmac_f32_e32 v61, v65, v57
	v_fma_f32 v48, -v49, v60, v50
	v_div_fmas_f32 v47, v47, v55, v59
	s_mov_b64 vcc, s[6:7]
	v_fmac_f32_e32 v62, v66, v58
	v_fma_f32 v49, -v51, v61, v52
	v_div_fixup_f32 v40, v47, v40, v39
	v_div_fmas_f32 v39, v48, v56, v60
	s_mov_b64 vcc, s[8:9]
	v_fma_f32 v50, -v53, v62, v54
	v_div_fixup_f32 v41, v39, v41, v42
	v_div_fmas_f32 v39, v49, v57, v61
	s_mov_b64 vcc, s[10:11]
	v_div_fixup_f32 v42, v39, v45, v43
	v_div_fmas_f32 v39, v50, v58, v62
	v_div_fixup_f32 v43, v39, v46, v44
	ds_write_b128 v38, v[40:43]
	v_add_u32_e32 v38, 16, v38
	v_mov_b32_e32 v39, v136
	v_mov_b32_e32 v42, v137
	v_mov_b32_e32 v43, v138
	v_mov_b32_e32 v44, v139
	s_waitcnt vmcnt(3)
	v_mul_f32_e32 v40, 0xbfb8aa3b, v39
	s_waitcnt vmcnt(2)
	v_mul_f32_e32 v41, 0xbfb8aa3b, v42
	v_exp_f32_e32 v40, v40
	s_waitcnt vmcnt(1)
	v_mul_f32_e32 v45, 0xbfb8aa3b, v43
	v_exp_f32_e32 v41, v41
	s_waitcnt vmcnt(0)
	v_mul_f32_e32 v46, 0xbfb8aa3b, v44
	v_exp_f32_e32 v45, v45
	v_exp_f32_e32 v46, v46
	v_add_f32_e32 v40, 1.0, v40
	v_add_f32_e32 v41, 1.0, v41
	v_div_scale_f32 v47, s[6:7], v40, v40, v39
	v_add_f32_e32 v45, 1.0, v45
	v_div_scale_f32 v49, s[6:7], v41, v41, v42
	v_rcp_f32_e32 v55, v47
	v_add_f32_e32 v46, 1.0, v46
	v_div_scale_f32 v51, s[8:9], v45, v45, v43
	v_rcp_f32_e32 v56, v49
	v_div_scale_f32 v53, s[10:11], v46, v46, v44
	v_rcp_f32_e32 v57, v51
	v_rcp_f32_e32 v58, v53
	v_fma_f32 v59, -v47, v55, 1.0
	v_div_scale_f32 v48, vcc, v39, v40, v39
	v_fma_f32 v60, -v49, v56, 1.0
	v_fmac_f32_e32 v55, v59, v55
	v_div_scale_f32 v50, s[6:7], v42, v41, v42
	v_fma_f32 v61, -v51, v57, 1.0
	v_fmac_f32_e32 v56, v60, v56
	v_mul_f32_e32 v59, v48, v55
	v_div_scale_f32 v52, s[8:9], v43, v45, v43
	v_fma_f32 v62, -v53, v58, 1.0
	v_fmac_f32_e32 v57, v61, v57
	v_mul_f32_e32 v60, v50, v56
	v_fma_f32 v63, -v47, v59, v48
	v_div_scale_f32 v54, s[10:11], v44, v46, v44
	v_fmac_f32_e32 v58, v62, v58
	v_mul_f32_e32 v61, v52, v57
	v_fma_f32 v64, -v49, v60, v50
	v_fmac_f32_e32 v59, v63, v55
	v_mul_f32_e32 v62, v54, v58
	v_fma_f32 v65, -v51, v61, v52
	v_fmac_f32_e32 v60, v64, v56
	v_fma_f32 v47, -v47, v59, v48
	v_fma_f32 v66, -v53, v62, v54
	v_fmac_f32_e32 v61, v65, v57
	v_fma_f32 v48, -v49, v60, v50
	v_div_fmas_f32 v47, v47, v55, v59
	s_mov_b64 vcc, s[6:7]
	v_fmac_f32_e32 v62, v66, v58
	v_fma_f32 v49, -v51, v61, v52
	v_div_fixup_f32 v40, v47, v40, v39
	v_div_fmas_f32 v39, v48, v56, v60
	s_mov_b64 vcc, s[8:9]
	v_fma_f32 v50, -v53, v62, v54
	v_div_fixup_f32 v41, v39, v41, v42
	v_div_fmas_f32 v39, v49, v57, v61
	s_mov_b64 vcc, s[10:11]
	v_div_fixup_f32 v42, v39, v45, v43
	v_div_fmas_f32 v39, v50, v58, v62
	v_div_fixup_f32 v43, v39, v46, v44
	ds_write_b128 v38, v[40:43]
	v_add_u32_e32 v38, 16, v38
	v_mov_b32_e32 v39, v140
	v_mov_b32_e32 v42, v141
	v_mov_b32_e32 v43, v142
	v_mov_b32_e32 v44, v143
	s_waitcnt vmcnt(3)
; DI void ada_item(int it, const float* cP, const float* cS, const float* wada, const float* bada, float* mod, LAS float* red, int tid, int wave, int lane) {
;     ...
;         for (int b = 0; b < 36; ++b) { const float cv = b < 4 ? cP[b * 1024 + kb + lane] : cS[(b - 4) * 1024 + kb + lane]; cs[lane * 36 + b] = cv / (1.f + __expf(-cv)); }
;         asm volatile("s_waitcnt lgkmcnt(0)" ::: "memory");
; #pragma unroll 1
;         for (int k8 = 0; k8 < 8; ++k8) {
;             float wv[8];
; #pragma unroll
;             for (int j = 0; j < 8; ++j) wv[j] = wada[(size_t)(kb + 8 * k8 + j) * NMOD + c0 + lane];
	v_mul_f32_e32 v40, 0xbfb8aa3b, v39
	s_waitcnt vmcnt(2)
	v_mul_f32_e32 v41, 0xbfb8aa3b, v42
	v_exp_f32_e32 v40, v40
	s_waitcnt vmcnt(1)
	v_mul_f32_e32 v45, 0xbfb8aa3b, v43
	v_exp_f32_e32 v41, v41
	s_waitcnt vmcnt(0)
	v_mul_f32_e32 v46, 0xbfb8aa3b, v44
	v_exp_f32_e32 v45, v45
	v_exp_f32_e32 v46, v46
	v_add_f32_e32 v40, 1.0, v40
	v_add_f32_e32 v41, 1.0, v41
	v_div_scale_f32 v47, s[6:7], v40, v40, v39
	v_add_f32_e32 v45, 1.0, v45
	v_div_scale_f32 v49, s[6:7], v41, v41, v42
	v_rcp_f32_e32 v55, v47
	v_add_f32_e32 v46, 1.0, v46
	v_div_scale_f32 v51, s[8:9], v45, v45, v43
	v_rcp_f32_e32 v56, v49
	v_div_scale_f32 v53, s[10:11], v46, v46, v44
	v_rcp_f32_e32 v57, v51
	v_rcp_f32_e32 v58, v53
	v_fma_f32 v59, -v47, v55, 1.0
	v_div_scale_f32 v48, vcc, v39, v40, v39
	v_fma_f32 v60, -v49, v56, 1.0
	v_fmac_f32_e32 v55, v59, v55
	v_div_scale_f32 v50, s[6:7], v42, v41, v42
	v_fma_f32 v61, -v51, v57, 1.0
	v_fmac_f32_e32 v56, v60, v56
	v_mul_f32_e32 v59, v48, v55
	v_div_scale_f32 v52, s[8:9], v43, v45, v43
	v_fma_f32 v62, -v53, v58, 1.0
	v_fmac_f32_e32 v57, v61, v57
	v_mul_f32_e32 v60, v50, v56
	v_fma_f32 v63, -v47, v59, v48
	v_div_scale_f32 v54, s[10:11], v44, v46, v44
	v_fmac_f32_e32 v58, v62, v58
	v_mul_f32_e32 v61, v52, v57
	v_fma_f32 v64, -v49, v60, v50
	v_fmac_f32_e32 v59, v63, v55
	v_mul_f32_e32 v62, v54, v58
	v_fma_f32 v65, -v51, v61, v52
	v_fmac_f32_e32 v60, v64, v56
	v_fma_f32 v47, -v47, v59, v48
	v_fma_f32 v66, -v53, v62, v54
	v_fmac_f32_e32 v61, v65, v57
	v_fma_f32 v48, -v49, v60, v50
	v_div_fmas_f32 v47, v47, v55, v59
	s_mov_b64 vcc, s[6:7]
	v_fmac_f32_e32 v62, v66, v58
	v_fma_f32 v49, -v51, v61, v52
	v_div_fixup_f32 v40, v47, v40, v39
	v_div_fmas_f32 v39, v48, v56, v60
	s_mov_b64 vcc, s[8:9]
	v_fma_f32 v50, -v53, v62, v54
	v_div_fixup_f32 v41, v39, v41, v42
	v_div_fmas_f32 v39, v49, v57, v61
	s_mov_b64 vcc, s[10:11]
	v_div_fixup_f32 v42, v39, v45, v43
	v_div_fmas_f32 v39, v50, v58, v62
	v_div_fixup_f32 v43, v39, v46, v44
	ds_write_b128 v38, v[40:43]
	v_add_u32_e32 v38, 16, v38
	v_mov_b32_e32 v39, v144
	v_mov_b32_e32 v42, v145
	v_mov_b32_e32 v43, v146
	v_mov_b32_e32 v44, v147
	s_waitcnt vmcnt(3)
	v_mul_f32_e32 v40, 0xbfb8aa3b, v39
	s_waitcnt vmcnt(2)
	v_mul_f32_e32 v41, 0xbfb8aa3b, v42
	v_exp_f32_e32 v40, v40
	s_waitcnt vmcnt(1)
	v_mul_f32_e32 v45, 0xbfb8aa3b, v43
	v_exp_f32_e32 v41, v41
	s_waitcnt vmcnt(0)
	v_mul_f32_e32 v46, 0xbfb8aa3b, v44
	v_exp_f32_e32 v45, v45
	v_exp_f32_e32 v46, v46
	v_add_f32_e32 v40, 1.0, v40
	v_add_f32_e32 v41, 1.0, v41
	v_div_scale_f32 v47, s[6:7], v40, v40, v39
	v_add_f32_e32 v45, 1.0, v45
	v_div_scale_f32 v49, s[6:7], v41, v41, v42
	v_rcp_f32_e32 v55, v47
	v_add_f32_e32 v46, 1.0, v46
	v_div_scale_f32 v51, s[8:9], v45, v45, v43
	v_rcp_f32_e32 v56, v49
	v_div_scale_f32 v53, s[10:11], v46, v46, v44
	v_rcp_f32_e32 v57, v51
	v_rcp_f32_e32 v58, v53
	v_fma_f32 v59, -v47, v55, 1.0
	v_div_scale_f32 v48, vcc, v39, v40, v39
	v_fma_f32 v60, -v49, v56, 1.0
	v_fmac_f32_e32 v55, v59, v55
	v_div_scale_f32 v50, s[6:7], v42, v41, v42
	v_fma_f32 v61, -v51, v57, 1.0
	v_fmac_f32_e32 v56, v60, v56
	v_mul_f32_e32 v59, v48, v55
	v_div_scale_f32 v52, s[8:9], v43, v45, v43
	v_fma_f32 v62, -v53, v58, 1.0
	v_fmac_f32_e32 v57, v61, v57
	v_mul_f32_e32 v60, v50, v56
	v_fma_f32 v63, -v47, v59, v48
	v_div_scale_f32 v54, s[10:11], v44, v46, v44
	v_fmac_f32_e32 v58, v62, v58
	v_mul_f32_e32 v61, v52, v57
	v_fma_f32 v64, -v49, v60, v50
	v_fmac_f32_e32 v59, v63, v55
	v_mul_f32_e32 v62, v54, v58
	v_fma_f32 v65, -v51, v61, v52
	v_fmac_f32_e32 v60, v64, v56
	v_fma_f32 v47, -v47, v59, v48
	v_fma_f32 v66, -v53, v62, v54
	v_fmac_f32_e32 v61, v65, v57
	v_fma_f32 v48, -v49, v60, v50
	v_div_fmas_f32 v47, v47, v55, v59
	s_mov_b64 vcc, s[6:7]
	v_fmac_f32_e32 v62, v66, v58
	v_fma_f32 v49, -v51, v61, v52
	v_div_fixup_f32 v40, v47, v40, v39
	v_div_fmas_f32 v39, v48, v56, v60
	s_mov_b64 vcc, s[8:9]
	v_fma_f32 v50, -v53, v62, v54
	v_div_fixup_f32 v41, v39, v41, v42
	v_div_fmas_f32 v39, v49, v57, v61
	s_mov_b64 vcc, s[10:11]
	v_div_fixup_f32 v42, v39, v45, v43
	v_div_fmas_f32 v39, v50, v58, v62
	v_div_fixup_f32 v43, v39, v46, v44
	ds_write_b128 v38, v[40:43]
	v_add_u32_e32 v38, 16, v38
	s_waitcnt lgkmcnt(0)
	v_mad_i64_i32 v[82:83], s[6:7], s13, v206, v[80:81]
	s_mov_b64 s[6:7], 0
	s_mov_b32 s8, s17
	s_mul_i32 s9, s13, 0x9000
	s_lshl_b32 s10, s12, 2
	s_add_u32 s9, s9, s10
	s_add_u32 s10, s62, s9
	s_addc_u32 s11, s63, 0
	v_lshrrev_b32_e32 v94, 4, v207
	v_and_b32_e32 v96, 15, v207
	v_mul_u32_u24_e32 v95, 0x9000, v94
	v_lshl_add_u32 v95, v96, 2, v95
	v_mul_u32_u24_e32 v94, 0x90, v94
	v_lshl_add_u32 v94, v96, 2, v94
	v_add_u32_e32 v94, s17, v94
	global_load_dword v36, v95, s[10:11]
	global_load_dword v37, v95, s[10:11] offset:64
	global_load_dword v38, v95, s[10:11] offset:128
	global_load_dword v39, v95, s[10:11] offset:192
	v_add_u32_e32 v95, 0x24000, v95
	global_load_dword v40, v95, s[10:11]
	global_load_dword v41, v95, s[10:11] offset:64
	global_load_dword v42, v95, s[10:11] offset:128
	global_load_dword v43, v95, s[10:11] offset:192
	v_add_u32_e32 v95, 0x24000, v95
	global_load_dword v44, v95, s[10:11]
	global_load_dword v45, v95, s[10:11] offset:64
	global_load_dword v46, v95, s[10:11] offset:128
	global_load_dword v47, v95, s[10:11] offset:192
	v_add_u32_e32 v95, 0x24000, v95
	global_load_dword v48, v95, s[10:11]
	global_load_dword v49, v95, s[10:11] offset:64
	global_load_dword v50, v95, s[10:11] offset:128
	global_load_dword v51, v95, s[10:11] offset:192
	v_add_u32_e32 v95, 0x24000, v95
	global_load_dword v52, v95, s[10:11]
	global_load_dword v53, v95, s[10:11] offset:64
	global_load_dword v54, v95, s[10:11] offset:128
	global_load_dword v55, v95, s[10:11] offset:192
; #define LAS __attribute__((address_space(3)))
; DI void ada_item(int it, const float* cP, const float* cS, const float* wada, const float* bada, float* mod, LAS float* red, int tid, int wave, int lane) {
;     ...
;         for (int k8 = 0; k8 < 8; ++k8) {
;             float wv[8];
; #pragma unroll
;             for (int j = 0; j < 8; ++j) wv[j] = wada[(size_t)(kb + 8 * k8 + j) * NMOD + c0 + lane];
; #pragma unroll
;             for (int j = 0; j < 8; ++j) {
;                 const LAS f32x4* cr = (const LAS f32x4*)(cs + (8 * k8 + j) * 36);
; #pragma unroll
;                 for (int q = 0; q < 9; ++q) { const f32x4 c4 = cr[q]; acc[4 * q] += c4[0] * wv[j]; acc[4 * q + 1] += c4[1] * wv[j]; acc[4 * q + 2] += c4[2] * wv[j]; acc[4 * q + 3] += c4[3] * wv[j]; }
	v_add_u32_e32 v95, 0x24000, v95
	global_load_dword v56, v95, s[10:11]
	global_load_dword v57, v95, s[10:11] offset:64
	global_load_dword v58, v95, s[10:11] offset:128
	global_load_dword v59, v95, s[10:11] offset:192
	v_add_u32_e32 v95, 0x24000, v95
	global_load_dword v60, v95, s[10:11]
	global_load_dword v61, v95, s[10:11] offset:64
	global_load_dword v62, v95, s[10:11] offset:128
	global_load_dword v63, v95, s[10:11] offset:192
	v_add_u32_e32 v95, 0x24000, v95
	global_load_dword v64, v95, s[10:11]
	global_load_dword v65, v95, s[10:11] offset:64
	global_load_dword v66, v95, s[10:11] offset:128
	global_load_dword v67, v95, s[10:11] offset:192
	v_add_u32_e32 v95, 0x24000, v95
	ds_read_b32 v112, v94
	ds_read_b32 v113, v94 offset:64
	ds_read_b32 v114, v94 offset:128
	ds_read_b32 v115, v94 offset:576
	ds_read_b32 v116, v94 offset:640
	ds_read_b32 v117, v94 offset:704
	ds_read_b32 v118, v94 offset:1152
	ds_read_b32 v119, v94 offset:1216
	ds_read_b32 v120, v94 offset:1280
	ds_read_b32 v121, v94 offset:1728
	ds_read_b32 v122, v94 offset:1792
	ds_read_b32 v123, v94 offset:1856
	ds_read_b32 v124, v94 offset:2304
	ds_read_b32 v125, v94 offset:2368
	ds_read_b32 v126, v94 offset:2432
	ds_read_b32 v127, v94 offset:2880
	ds_read_b32 v128, v94 offset:2944
	ds_read_b32 v129, v94 offset:3008
	ds_read_b32 v130, v94 offset:3456
	ds_read_b32 v131, v94 offset:3520
	ds_read_b32 v132, v94 offset:3584
	ds_read_b32 v133, v94 offset:4032
	ds_read_b32 v134, v94 offset:4096
	ds_read_b32 v135, v94 offset:4160
	ds_read_b32 v136, v94 offset:4608
	ds_read_b32 v137, v94 offset:4672
	ds_read_b32 v138, v94 offset:4736
	ds_read_b32 v139, v94 offset:5184
	ds_read_b32 v140, v94 offset:5248
	ds_read_b32 v141, v94 offset:5312
	ds_read_b32 v142, v94 offset:5760
	ds_read_b32 v143, v94 offset:5824
	ds_read_b32 v144, v94 offset:5888
	ds_read_b32 v145, v94 offset:6336
	ds_read_b32 v146, v94 offset:6400
	ds_read_b32 v147, v94 offset:6464
	ds_read_b32 v148, v94 offset:6912
	ds_read_b32 v149, v94 offset:6976
	ds_read_b32 v150, v94 offset:7040
	ds_read_b32 v151, v94 offset:7488
	ds_read_b32 v152, v94 offset:7552
	ds_read_b32 v153, v94 offset:7616
	ds_read_b32 v154, v94 offset:8064
	ds_read_b32 v155, v94 offset:8128
	ds_read_b32 v156, v94 offset:8192
	ds_read_b32 v157, v94 offset:8640
	ds_read_b32 v158, v94 offset:8704
	ds_read_b32 v159, v94 offset:8768
	s_waitcnt vmcnt(28) lgkmcnt(15)
	v_mfma_f32_16x16x4_f32 v[0:3], v112, v36, v[0:3]
	v_mfma_f32_16x16x4_f32 v[4:7], v112, v37, v[4:7]
	v_mfma_f32_16x16x4_f32 v[8:11], v112, v38, v[8:11]
	v_mfma_f32_16x16x4_f32 v[12:15], v112, v39, v[12:15]
	v_mfma_f32_16x16x4_f32 v[16:19], v113, v36, v[16:19]
	v_mfma_f32_16x16x4_f32 v[20:23], v113, v37, v[20:23]
	v_mfma_f32_16x16x4_f32 v[24:27], v113, v38, v[24:27]
	v_mfma_f32_16x16x4_f32 v[28:31], v113, v39, v[28:31]
	v_mfma_f32_16x16x4_f32 v[32:35], v114, v36, v[32:35]
	v_mfma_f32_16x16x4_f32 v[100:103], v114, v37, v[100:103]
	v_mfma_f32_16x16x4_f32 v[104:107], v114, v38, v[104:107]
	v_mfma_f32_16x16x4_f32 v[108:111], v114, v39, v[108:111]
	global_load_dword v36, v95, s[10:11]
	global_load_dword v37, v95, s[10:11] offset:64
	global_load_dword v38, v95, s[10:11] offset:128
	global_load_dword v39, v95, s[10:11] offset:192
	v_add_u32_e32 v95, 0x24000, v95
	s_waitcnt vmcnt(28) lgkmcnt(15)
	v_mfma_f32_16x16x4_f32 v[0:3], v115, v40, v[0:3]
	v_mfma_f32_16x16x4_f32 v[4:7], v115, v41, v[4:7]
	v_mfma_f32_16x16x4_f32 v[8:11], v115, v42, v[8:11]
	v_mfma_f32_16x16x4_f32 v[12:15], v115, v43, v[12:15]
	v_mfma_f32_16x16x4_f32 v[16:19], v116, v40, v[16:19]
	v_mfma_f32_16x16x4_f32 v[20:23], v116, v41, v[20:23]
	v_mfma_f32_16x16x4_f32 v[24:27], v116, v42, v[24:27]
	v_mfma_f32_16x16x4_f32 v[28:31], v116, v43, v[28:31]
	v_mfma_f32_16x16x4_f32 v[32:35], v117, v40, v[32:35]
	v_mfma_f32_16x16x4_f32 v[100:103], v117, v41, v[100:103]
	v_mfma_f32_16x16x4_f32 v[104:107], v117, v42, v[104:107]
	v_mfma_f32_16x16x4_f32 v[108:111], v117, v43, v[108:111]
	global_load_dword v40, v95, s[10:11]
	global_load_dword v41, v95, s[10:11] offset:64
	global_load_dword v42, v95, s[10:11] offset:128
	global_load_dword v43, v95, s[10:11] offset:192
	v_add_u32_e32 v95, 0x24000, v95
	s_waitcnt vmcnt(28) lgkmcnt(15)
	v_mfma_f32_16x16x4_f32 v[0:3], v118, v44, v[0:3]
	v_mfma_f32_16x16x4_f32 v[4:7], v118, v45, v[4:7]
	v_mfma_f32_16x16x4_f32 v[8:11], v118, v46, v[8:11]
	v_mfma_f32_16x16x4_f32 v[12:15], v118, v47, v[12:15]
	v_mfma_f32_16x16x4_f32 v[16:19], v119, v44, v[16:19]
	v_mfma_f32_16x16x4_f32 v[20:23], v119, v45, v[20:23]
	v_mfma_f32_16x16x4_f32 v[24:27], v119, v46, v[24:27]
	v_mfma_f32_16x16x4_f32 v[28:31], v119, v47, v[28:31]
	v_mfma_f32_16x16x4_f32 v[32:35], v120, v44, v[32:35]
	v_mfma_f32_16x16x4_f32 v[100:103], v120, v45, v[100:103]
	v_mfma_f32_16x16x4_f32 v[104:107], v120, v46, v[104:107]
	v_mfma_f32_16x16x4_f32 v[108:111], v120, v47, v[108:111]
	global_load_dword v44, v95, s[10:11]
	global_load_dword v45, v95, s[10:11] offset:64
	global_load_dword v46, v95, s[10:11] offset:128
	global_load_dword v47, v95, s[10:11] offset:192
	v_add_u32_e32 v95, 0x24000, v95
	s_waitcnt vmcnt(28) lgkmcnt(15)
	v_mfma_f32_16x16x4_f32 v[0:3], v121, v48, v[0:3]
	v_mfma_f32_16x16x4_f32 v[4:7], v121, v49, v[4:7]
	v_mfma_f32_16x16x4_f32 v[8:11], v121, v50, v[8:11]
	v_mfma_f32_16x16x4_f32 v[12:15], v121, v51, v[12:15]
	v_mfma_f32_16x16x4_f32 v[16:19], v122, v48, v[16:19]
	v_mfma_f32_16x16x4_f32 v[20:23], v122, v49, v[20:23]
	v_mfma_f32_16x16x4_f32 v[24:27], v122, v50, v[24:27]
	v_mfma_f32_16x16x4_f32 v[28:31], v122, v51, v[28:31]
	v_mfma_f32_16x16x4_f32 v[32:35], v123, v48, v[32:35]
	v_mfma_f32_16x16x4_f32 v[100:103], v123, v49, v[100:103]
	v_mfma_f32_16x16x4_f32 v[104:107], v123, v50, v[104:107]
	v_mfma_f32_16x16x4_f32 v[108:111], v123, v51, v[108:111]
	global_load_dword v48, v95, s[10:11]
	global_load_dword v49, v95, s[10:11] offset:64
	global_load_dword v50, v95, s[10:11] offset:128
	global_load_dword v51, v95, s[10:11] offset:192
	v_add_u32_e32 v95, 0x24000, v95
	s_waitcnt vmcnt(28) lgkmcnt(15)
; #define LAS __attribute__((address_space(3)))
; DI void ada_item(int it, const float* cP, const float* cS, const float* wada, const float* bada, float* mod, LAS float* red, int tid, int wave, int lane) {
;     ...
; #pragma unroll
;             for (int j = 0; j < 8; ++j) {
;                 const LAS f32x4* cr = (const LAS f32x4*)(cs + (8 * k8 + j) * 36);
; #pragma unroll
;                 for (int q = 0; q < 9; ++q) { const f32x4 c4 = cr[q]; acc[4 * q] += c4[0] * wv[j]; acc[4 * q + 1] += c4[1] * wv[j]; acc[4 * q + 2] += c4[2] * wv[j]; acc[4 * q + 3] += c4[3] * wv[j]; }
	v_mfma_f32_16x16x4_f32 v[0:3], v124, v52, v[0:3]
	v_mfma_f32_16x16x4_f32 v[4:7], v124, v53, v[4:7]
	v_mfma_f32_16x16x4_f32 v[8:11], v124, v54, v[8:11]
	v_mfma_f32_16x16x4_f32 v[12:15], v124, v55, v[12:15]
	v_mfma_f32_16x16x4_f32 v[16:19], v125, v52, v[16:19]
	v_mfma_f32_16x16x4_f32 v[20:23], v125, v53, v[20:23]
	v_mfma_f32_16x16x4_f32 v[24:27], v125, v54, v[24:27]
	v_mfma_f32_16x16x4_f32 v[28:31], v125, v55, v[28:31]
	v_mfma_f32_16x16x4_f32 v[32:35], v126, v52, v[32:35]
	v_mfma_f32_16x16x4_f32 v[100:103], v126, v53, v[100:103]
	v_mfma_f32_16x16x4_f32 v[104:107], v126, v54, v[104:107]
	v_mfma_f32_16x16x4_f32 v[108:111], v126, v55, v[108:111]
	global_load_dword v52, v95, s[10:11]
	global_load_dword v53, v95, s[10:11] offset:64
	global_load_dword v54, v95, s[10:11] offset:128
	global_load_dword v55, v95, s[10:11] offset:192
	v_add_u32_e32 v95, 0x24000, v95
	s_waitcnt vmcnt(28) lgkmcnt(15)
	v_mfma_f32_16x16x4_f32 v[0:3], v127, v56, v[0:3]
	v_mfma_f32_16x16x4_f32 v[4:7], v127, v57, v[4:7]
	v_mfma_f32_16x16x4_f32 v[8:11], v127, v58, v[8:11]
	v_mfma_f32_16x16x4_f32 v[12:15], v127, v59, v[12:15]
	v_mfma_f32_16x16x4_f32 v[16:19], v128, v56, v[16:19]
	v_mfma_f32_16x16x4_f32 v[20:23], v128, v57, v[20:23]
	v_mfma_f32_16x16x4_f32 v[24:27], v128, v58, v[24:27]
	v_mfma_f32_16x16x4_f32 v[28:31], v128, v59, v[28:31]
	v_mfma_f32_16x16x4_f32 v[32:35], v129, v56, v[32:35]
	v_mfma_f32_16x16x4_f32 v[100:103], v129, v57, v[100:103]
	v_mfma_f32_16x16x4_f32 v[104:107], v129, v58, v[104:107]
	v_mfma_f32_16x16x4_f32 v[108:111], v129, v59, v[108:111]
	global_load_dword v56, v95, s[10:11]
	global_load_dword v57, v95, s[10:11] offset:64
	global_load_dword v58, v95, s[10:11] offset:128
	global_load_dword v59, v95, s[10:11] offset:192
	v_add_u32_e32 v95, 0x24000, v95
	s_waitcnt vmcnt(28) lgkmcnt(15)
	v_mfma_f32_16x16x4_f32 v[0:3], v130, v60, v[0:3]
	v_mfma_f32_16x16x4_f32 v[4:7], v130, v61, v[4:7]
	v_mfma_f32_16x16x4_f32 v[8:11], v130, v62, v[8:11]
	v_mfma_f32_16x16x4_f32 v[12:15], v130, v63, v[12:15]
	v_mfma_f32_16x16x4_f32 v[16:19], v131, v60, v[16:19]
	v_mfma_f32_16x16x4_f32 v[20:23], v131, v61, v[20:23]
	v_mfma_f32_16x16x4_f32 v[24:27], v131, v62, v[24:27]
	v_mfma_f32_16x16x4_f32 v[28:31], v131, v63, v[28:31]
	v_mfma_f32_16x16x4_f32 v[32:35], v132, v60, v[32:35]
	v_mfma_f32_16x16x4_f32 v[100:103], v132, v61, v[100:103]
	v_mfma_f32_16x16x4_f32 v[104:107], v132, v62, v[104:107]
	v_mfma_f32_16x16x4_f32 v[108:111], v132, v63, v[108:111]
	global_load_dword v60, v95, s[10:11]
	global_load_dword v61, v95, s[10:11] offset:64
	global_load_dword v62, v95, s[10:11] offset:128
	global_load_dword v63, v95, s[10:11] offset:192
	v_add_u32_e32 v95, 0x24000, v95
	s_waitcnt vmcnt(28) lgkmcnt(15)
	v_mfma_f32_16x16x4_f32 v[0:3], v133, v64, v[0:3]
	v_mfma_f32_16x16x4_f32 v[4:7], v133, v65, v[4:7]
	v_mfma_f32_16x16x4_f32 v[8:11], v133, v66, v[8:11]
	v_mfma_f32_16x16x4_f32 v[12:15], v133, v67, v[12:15]
	v_mfma_f32_16x16x4_f32 v[16:19], v134, v64, v[16:19]
	v_mfma_f32_16x16x4_f32 v[20:23], v134, v65, v[20:23]
	v_mfma_f32_16x16x4_f32 v[24:27], v134, v66, v[24:27]
	v_mfma_f32_16x16x4_f32 v[28:31], v134, v67, v[28:31]
	v_mfma_f32_16x16x4_f32 v[32:35], v135, v64, v[32:35]
	v_mfma_f32_16x16x4_f32 v[100:103], v135, v65, v[100:103]
	v_mfma_f32_16x16x4_f32 v[104:107], v135, v66, v[104:107]
	v_mfma_f32_16x16x4_f32 v[108:111], v135, v67, v[108:111]
	global_load_dword v64, v95, s[10:11]
	global_load_dword v65, v95, s[10:11] offset:64
	global_load_dword v66, v95, s[10:11] offset:128
	global_load_dword v67, v95, s[10:11] offset:192
	v_add_u32_e32 v95, 0x24000, v95
	s_waitcnt vmcnt(28) lgkmcnt(15)
	v_mfma_f32_16x16x4_f32 v[0:3], v136, v36, v[0:3]
	v_mfma_f32_16x16x4_f32 v[4:7], v136, v37, v[4:7]
	v_mfma_f32_16x16x4_f32 v[8:11], v136, v38, v[8:11]
	v_mfma_f32_16x16x4_f32 v[12:15], v136, v39, v[12:15]
	v_mfma_f32_16x16x4_f32 v[16:19], v137, v36, v[16:19]
	v_mfma_f32_16x16x4_f32 v[20:23], v137, v37, v[20:23]
	v_mfma_f32_16x16x4_f32 v[24:27], v137, v38, v[24:27]
	v_mfma_f32_16x16x4_f32 v[28:31], v137, v39, v[28:31]
	v_mfma_f32_16x16x4_f32 v[32:35], v138, v36, v[32:35]
	v_mfma_f32_16x16x4_f32 v[100:103], v138, v37, v[100:103]
	v_mfma_f32_16x16x4_f32 v[104:107], v138, v38, v[104:107]
	v_mfma_f32_16x16x4_f32 v[108:111], v138, v39, v[108:111]
	s_waitcnt vmcnt(24) lgkmcnt(15)
	v_mfma_f32_16x16x4_f32 v[0:3], v139, v40, v[0:3]
	v_mfma_f32_16x16x4_f32 v[4:7], v139, v41, v[4:7]
	v_mfma_f32_16x16x4_f32 v[8:11], v139, v42, v[8:11]
	v_mfma_f32_16x16x4_f32 v[12:15], v139, v43, v[12:15]
	v_mfma_f32_16x16x4_f32 v[16:19], v140, v40, v[16:19]
	v_mfma_f32_16x16x4_f32 v[20:23], v140, v41, v[20:23]
	v_mfma_f32_16x16x4_f32 v[24:27], v140, v42, v[24:27]
	v_mfma_f32_16x16x4_f32 v[28:31], v140, v43, v[28:31]
	v_mfma_f32_16x16x4_f32 v[32:35], v141, v40, v[32:35]
	v_mfma_f32_16x16x4_f32 v[100:103], v141, v41, v[100:103]
	v_mfma_f32_16x16x4_f32 v[104:107], v141, v42, v[104:107]
	v_mfma_f32_16x16x4_f32 v[108:111], v141, v43, v[108:111]
	s_waitcnt vmcnt(20) lgkmcnt(15)
	v_mfma_f32_16x16x4_f32 v[0:3], v142, v44, v[0:3]
	v_mfma_f32_16x16x4_f32 v[4:7], v142, v45, v[4:7]
	v_mfma_f32_16x16x4_f32 v[8:11], v142, v46, v[8:11]
	v_mfma_f32_16x16x4_f32 v[12:15], v142, v47, v[12:15]
	v_mfma_f32_16x16x4_f32 v[16:19], v143, v44, v[16:19]
	v_mfma_f32_16x16x4_f32 v[20:23], v143, v45, v[20:23]
	v_mfma_f32_16x16x4_f32 v[24:27], v143, v46, v[24:27]
	v_mfma_f32_16x16x4_f32 v[28:31], v143, v47, v[28:31]
	v_mfma_f32_16x16x4_f32 v[32:35], v144, v44, v[32:35]
	v_mfma_f32_16x16x4_f32 v[100:103], v144, v45, v[100:103]
	v_mfma_f32_16x16x4_f32 v[104:107], v144, v46, v[104:107]
	v_mfma_f32_16x16x4_f32 v[108:111], v144, v47, v[108:111]
	s_waitcnt vmcnt(16) lgkmcnt(12)
; #define LAS __attribute__((address_space(3)))
; DI void ada_item(int it, const float* cP, const float* cS, const float* wada, const float* bada, float* mod, LAS float* red, int tid, int wave, int lane) {
;     ...
; #pragma unroll
;             for (int j = 0; j < 8; ++j) {
;                 const LAS f32x4* cr = (const LAS f32x4*)(cs + (8 * k8 + j) * 36);
; #pragma unroll
;                 for (int q = 0; q < 9; ++q) { const f32x4 c4 = cr[q]; acc[4 * q] += c4[0] * wv[j]; acc[4 * q + 1] += c4[1] * wv[j]; acc[4 * q + 2] += c4[2] * wv[j]; acc[4 * q + 3] += c4[3] * wv[j]; }
;             }
;         }
;         asm volatile("s_waitcnt lgkmcnt(0)" ::: "memory");
;     }
;     __syncthreads();
; #pragma unroll
;     for (int b = 0; b < 36; ++b) red[(wave * 36 + b) * 64 + lane] = acc[b];
;     __syncthreads();
;     for (int o = tid; o < 36 * 64; o += 512) {
;         const int b = o >> 6, l = o & 63; float s = 0.f;
; #pragma unroll
;         for (int w = 0; w < 8; ++w) s += red[(w * 36 + b) * 64 + l];
;         mod[(size_t)b * NMOD + c0 + l] = s + bada[c0 + l];
;     }
	v_mfma_f32_16x16x4_f32 v[0:3], v145, v48, v[0:3]
	v_mfma_f32_16x16x4_f32 v[4:7], v145, v49, v[4:7]
	v_mfma_f32_16x16x4_f32 v[8:11], v145, v50, v[8:11]
	v_mfma_f32_16x16x4_f32 v[12:15], v145, v51, v[12:15]
	v_mfma_f32_16x16x4_f32 v[16:19], v146, v48, v[16:19]
	v_mfma_f32_16x16x4_f32 v[20:23], v146, v49, v[20:23]
	v_mfma_f32_16x16x4_f32 v[24:27], v146, v50, v[24:27]
	v_mfma_f32_16x16x4_f32 v[28:31], v146, v51, v[28:31]
	v_mfma_f32_16x16x4_f32 v[32:35], v147, v48, v[32:35]
	v_mfma_f32_16x16x4_f32 v[100:103], v147, v49, v[100:103]
	v_mfma_f32_16x16x4_f32 v[104:107], v147, v50, v[104:107]
	v_mfma_f32_16x16x4_f32 v[108:111], v147, v51, v[108:111]
	s_waitcnt vmcnt(12) lgkmcnt(9)
	v_mfma_f32_16x16x4_f32 v[0:3], v148, v52, v[0:3]
	v_mfma_f32_16x16x4_f32 v[4:7], v148, v53, v[4:7]
	v_mfma_f32_16x16x4_f32 v[8:11], v148, v54, v[8:11]
	v_mfma_f32_16x16x4_f32 v[12:15], v148, v55, v[12:15]
	v_mfma_f32_16x16x4_f32 v[16:19], v149, v52, v[16:19]
	v_mfma_f32_16x16x4_f32 v[20:23], v149, v53, v[20:23]
	v_mfma_f32_16x16x4_f32 v[24:27], v149, v54, v[24:27]
	v_mfma_f32_16x16x4_f32 v[28:31], v149, v55, v[28:31]
	v_mfma_f32_16x16x4_f32 v[32:35], v150, v52, v[32:35]
	v_mfma_f32_16x16x4_f32 v[100:103], v150, v53, v[100:103]
	v_mfma_f32_16x16x4_f32 v[104:107], v150, v54, v[104:107]
	v_mfma_f32_16x16x4_f32 v[108:111], v150, v55, v[108:111]
	s_waitcnt vmcnt(8) lgkmcnt(6)
	v_mfma_f32_16x16x4_f32 v[0:3], v151, v56, v[0:3]
	v_mfma_f32_16x16x4_f32 v[4:7], v151, v57, v[4:7]
	v_mfma_f32_16x16x4_f32 v[8:11], v151, v58, v[8:11]
	v_mfma_f32_16x16x4_f32 v[12:15], v151, v59, v[12:15]
	v_mfma_f32_16x16x4_f32 v[16:19], v152, v56, v[16:19]
	v_mfma_f32_16x16x4_f32 v[20:23], v152, v57, v[20:23]
	v_mfma_f32_16x16x4_f32 v[24:27], v152, v58, v[24:27]
	v_mfma_f32_16x16x4_f32 v[28:31], v152, v59, v[28:31]
	v_mfma_f32_16x16x4_f32 v[32:35], v153, v56, v[32:35]
	v_mfma_f32_16x16x4_f32 v[100:103], v153, v57, v[100:103]
	v_mfma_f32_16x16x4_f32 v[104:107], v153, v58, v[104:107]
	v_mfma_f32_16x16x4_f32 v[108:111], v153, v59, v[108:111]
	s_waitcnt vmcnt(4) lgkmcnt(3)
	v_mfma_f32_16x16x4_f32 v[0:3], v154, v60, v[0:3]
	v_mfma_f32_16x16x4_f32 v[4:7], v154, v61, v[4:7]
	v_mfma_f32_16x16x4_f32 v[8:11], v154, v62, v[8:11]
	v_mfma_f32_16x16x4_f32 v[12:15], v154, v63, v[12:15]
	v_mfma_f32_16x16x4_f32 v[16:19], v155, v60, v[16:19]
	v_mfma_f32_16x16x4_f32 v[20:23], v155, v61, v[20:23]
	v_mfma_f32_16x16x4_f32 v[24:27], v155, v62, v[24:27]
	v_mfma_f32_16x16x4_f32 v[28:31], v155, v63, v[28:31]
	v_mfma_f32_16x16x4_f32 v[32:35], v156, v60, v[32:35]
	v_mfma_f32_16x16x4_f32 v[100:103], v156, v61, v[100:103]
	v_mfma_f32_16x16x4_f32 v[104:107], v156, v62, v[104:107]
	v_mfma_f32_16x16x4_f32 v[108:111], v156, v63, v[108:111]
	s_waitcnt vmcnt(0) lgkmcnt(0)
	v_mfma_f32_16x16x4_f32 v[0:3], v157, v64, v[0:3]
	v_mfma_f32_16x16x4_f32 v[4:7], v157, v65, v[4:7]
	v_mfma_f32_16x16x4_f32 v[8:11], v157, v66, v[8:11]
	v_mfma_f32_16x16x4_f32 v[12:15], v157, v67, v[12:15]
	v_mfma_f32_16x16x4_f32 v[16:19], v158, v64, v[16:19]
	v_mfma_f32_16x16x4_f32 v[20:23], v158, v65, v[20:23]
	v_mfma_f32_16x16x4_f32 v[24:27], v158, v66, v[24:27]
	v_mfma_f32_16x16x4_f32 v[28:31], v158, v67, v[28:31]
	v_mfma_f32_16x16x4_f32 v[32:35], v159, v64, v[32:35]
	v_mfma_f32_16x16x4_f32 v[100:103], v159, v65, v[100:103]
	v_mfma_f32_16x16x4_f32 v[104:107], v159, v66, v[104:107]
	v_mfma_f32_16x16x4_f32 v[108:111], v159, v67, v[108:111]
	s_waitcnt lgkmcnt(0)
	s_mov_b32 s8, 64
	s_mov_b64 s[6:7], 0
	s_and_b64 vcc, exec, s[14:15]
	s_cbranch_vccz .LBB0_706
	v_lshrrev_b32_e32 v36, 4, v207
	v_and_b32_e32 v37, 15, v207
	v_lshlrev_b32_e32 v36, 10, v36
	v_lshl_add_u32 v36, v37, 2, v36
	v_add_u32_e32 v36, s16, v36
	s_nop 15
	s_barrier
	ds_write_b32 v36, v0
	ds_write_b32 v36, v1 offset:256
	ds_write_b32 v36, v2 offset:512
	ds_write_b32 v36, v3 offset:768
	ds_write_b32 v36, v4 offset:64
	ds_write_b32 v36, v5 offset:320
	ds_write_b32 v36, v6 offset:576
	ds_write_b32 v36, v7 offset:832
	ds_write_b32 v36, v8 offset:128
	ds_write_b32 v36, v9 offset:384
	ds_write_b32 v36, v10 offset:640
	ds_write_b32 v36, v11 offset:896
	ds_write_b32 v36, v12 offset:192
	ds_write_b32 v36, v13 offset:448
	ds_write_b32 v36, v14 offset:704
	ds_write_b32 v36, v15 offset:960
	ds_write_b32 v36, v16 offset:4096
	ds_write_b32 v36, v17 offset:4352
	ds_write_b32 v36, v18 offset:4608
	ds_write_b32 v36, v19 offset:4864
	ds_write_b32 v36, v20 offset:4160
	ds_write_b32 v36, v21 offset:4416
	ds_write_b32 v36, v22 offset:4672
	ds_write_b32 v36, v23 offset:4928
	ds_write_b32 v36, v24 offset:4224
	ds_write_b32 v36, v25 offset:4480
	ds_write_b32 v36, v26 offset:4736
	ds_write_b32 v36, v27 offset:4992
	ds_write_b32 v36, v28 offset:4288
	ds_write_b32 v36, v29 offset:4544
	ds_write_b32 v36, v30 offset:4800
	ds_write_b32 v36, v31 offset:5056
	s_mov_b64 exec, 0xffff
	ds_write_b32 v36, v32 offset:8192
	ds_write_b32 v36, v33 offset:8448
	ds_write_b32 v36, v34 offset:8704
	ds_write_b32 v36, v35 offset:8960
	ds_write_b32 v36, v100 offset:8256
	ds_write_b32 v36, v101 offset:8512
	ds_write_b32 v36, v102 offset:8768
	ds_write_b32 v36, v103 offset:9024
	ds_write_b32 v36, v104 offset:8320
	ds_write_b32 v36, v105 offset:8576
	ds_write_b32 v36, v106 offset:8832
	ds_write_b32 v36, v107 offset:9088
	ds_write_b32 v36, v108 offset:8384
	ds_write_b32 v36, v109 offset:8640
	ds_write_b32 v36, v110 offset:8896
	ds_write_b32 v36, v111 offset:9152
	s_mov_b64 exec, -1
	s_waitcnt lgkmcnt(0)
	s_barrier
	s_and_saveexec_b64 s[6:7], s[4:5]
	s_cbranch_execz .LBB0_704
	s_lshl_b32 s8, s19, 6
	v_readlane_b32 s84, v253, 0
	v_or_b32_e32 v0, s8, v207
	v_readlane_b32 s88, v253, 4
	v_readlane_b32 s89, v253, 5
	v_readlane_b32 s90, v253, 6
	v_readlane_b32 s91, v253, 7
	v_readlane_b32 s94, v253, 10
	v_readlane_b32 s95, v253, 11
	v_readlane_b32 s98, v253, 14
	v_readlane_b32 s99, v253, 15
	s_ashr_i32 s9, s8, 31
	v_ashrrev_i32_e32 v1, 31, v0
	v_readlane_b32 s85, v253, 1
	v_readlane_b32 s92, v253, 8
	v_readlane_b32 s93, v253, 9
	v_readlane_b32 s96, v253, 12
	v_readlane_b32 s97, v253, 13
	v_readlane_b32 s98, v255, 39
	v_readlane_b32 s94, v255, 37
	v_readlane_b32 s88, v255, 27
	s_mov_b64 s[96:97], 0x800
	v_readlane_b32 s99, v255, 40
	v_readlane_b32 s95, v255, 38
	v_readlane_b32 s92, v255, 31
	v_readlane_b32 s89, v255, 28
	v_readlane_b32 s90, v255, 29
	v_readlane_b32 s91, v255, 30
	v_lshl_add_u64 v[0:1], v[0:1], 2, s[84:85]
	v_lshl_add_u64 v[2:3], s[8:9], 2, v[76:77]
	s_mov_b64 s[8:9], 0
	v_mov_b32_e32 v4, v172
	v_readlane_b32 s86, v253, 2
	v_readlane_b32 s87, v253, 3
	v_readlane_b32 s93, v255, 32
